# S5 pass C: initial-state loads of both directions requested at task start (ahead of the U and table loads) instead of a load + full wait at each direction's start
# baseline (speedup 1.0000x reference)
.Lxbn3_end:
.LBB0_1083:
	s_or_b64 exec, exec, s[4:5]
	s_mov_b64 s[52:53], s[0:1]
	s_waitcnt lgkmcnt(0)
	v_mov_b32_e32 v0, v170
	s_barrier
	s_movk_i32 s4, 0x1800
	v_ashrrev_i32_e32 v1, 6, v0
	v_add_u32_e32 v133, s46, v1
	v_cmp_gt_i32_e32 vcc, s4, v133
	s_and_saveexec_b64 s[54:55], vcc
	s_cbranch_execz .LBB0_1118
	s_load_dwordx2 s[6:7], s[52:53], 0xe8
	s_load_dwordx2 s[78:79], s[52:53], 0x20
	v_and_b32_e32 v4, 63, v0
	v_mov_b32_e32 v121, 0
	s_movk_i32 s4, 0x4400
	v_lshlrev_b32_e32 v122, 4, v4
	s_waitcnt lgkmcnt(0)
	s_add_u32 s56, s6, 0x9f9c000
	v_mov_b32_e32 v123, v121
	v_bfe_u32 v5, v0, 4, 2
	v_mul_lo_u32 v1, v1, s4
	s_addc_u32 s57, s7, 0
	v_lshl_add_u64 v[2:3], s[6:7], 0, v[122:123]
	s_mov_b64 s[8:9], 0x76d8000
	v_lshrrev_b32_e32 v6, 6, v0
	v_and_b32_e32 v177, 15, v0
	v_add_u32_e32 v1, 0, v1
	v_lshlrev_b32_e32 v120, 3, v5
	s_add_u32 s58, s6, 0x76c8000
	v_lshl_add_u64 v[124:125], v[2:3], 0, s[8:9]
	s_mov_b64 s[8:9], 0x7758000
	v_lshlrev_b32_e32 v128, 3, v4
	v_mov_b32_e32 v129, v121
	v_and_b32_e32 v0, 48, v0
	v_cmp_gt_u32_e64 s[4:5], 32, v4
	s_addc_u32 s59, s7, 0
	v_lshl_add_u64 v[126:127], v[2:3], 0, s[8:9]
	v_lshl_add_u64 v[2:3], s[6:7], 0, v[128:129]
	v_lshlrev_b32_e32 v132, 1, v4
	v_add_u32_e32 v8, v1, v0
	v_lshlrev_b32_e32 v0, 2, v5
	v_lshl_add_u64 v[4:5], s[6:7], 0, v[120:121]
	s_mov_b64 s[6:7], 0xbd9c000
	s_mov_b64 s[8:9], 0xb79c000
	v_add_u32_e32 v7, v1, v120
	v_mul_u32_u24_e32 v9, 0x110, v177
	v_lshl_add_u64 v[134:135], v[4:5], 0, s[6:7]
	s_mov_b64 s[6:7], 0xb79c200
	s_mov_b32 s64, 0xfff80000
	v_lshl_add_u64 v[130:131], v[2:3], 0, s[8:9]
	v_add_u32_e32 v123, v1, v132
	v_add_u16_e32 v178, s46, v6
	v_lshl_add_u64 v[136:137], v[2:3], 0, s[6:7]
	s_mov_b64 s[60:61], 0
	v_lshlrev_b32_e32 v138, 2, v120
	s_movk_i32 s45, 0x1000
	s_mov_b64 s[62:63], 0x80000
	s_mov_b32 s65, -1
	v_lshlrev_b32_e32 v140, 2, v0
	s_movk_i32 s47, 0x17ff
	v_mov_b32_e32 v139, v121
	v_add_u32_e32 v179, v7, v9
	v_add_u32_e32 v180, v8, v9
	s_branch .LBB0_1086

.LBB0_1086:
	v_ashrrev_i32_e32 v0, 5, v133
	v_cmp_lt_i32_e64 s[6:7], 63, v0
	v_cmp_gt_i32_e32 vcc, 64, v0
	s_and_saveexec_b64 s[8:9], vcc
	s_xor_b64 s[8:9], exec, s[8:9]
	v_ashrrev_i32_e32 v152, 7, v133
	v_bfe_u32 v141, v133, 5, 2
	v_and_b32_e32 v154, -4, v0
	s_or_saveexec_b64 s[8:9], s[8:9]
	v_mov_b32_e32 v181, 4
	s_xor_b64 exec, exec, s[8:9]
	v_subrev_u32_e32 v1, 64, v0
	v_lshrrev_b32_e32 v152, 5, v1
	v_and_b32_e32 v1, 0xffffffe0, v1
	v_bfe_u32 v141, v133, 5, 5
	v_add_u32_e32 v154, 64, v1
	v_mov_b32_e32 v181, 32
	s_or_b64 exec, exec, s[8:9]
	v_and_b32_e32 v183, 31, v133
	v_lshlrev_b32_e32 v120, 6, v183
	v_lshl_or_b32 v148, v0, 6, v177
	v_lshl_add_u64 v[150:151], s[56:57], 0, v[120:121]
	v_lshl_add_u64 v[0:1], v[150:151], 0, v[138:139]
	v_ashrrev_i32_e32 v149, 31, v148
	v_or_b32_e32 v146, 16, v148
	v_or_b32_e32 v144, 32, v148
	v_or_b32_e32 v142, 48, v148
	v_ashrrev_i32_e32 v147, 31, v146
	v_ashrrev_i32_e32 v145, 31, v144
	v_ashrrev_i32_e32 v143, 31, v142
	v_mov_b32_e32 v48, 0
	v_mov_b32_e32 v49, 0
	v_mov_b32_e32 v50, 0
	v_mov_b32_e32 v51, 0
	v_mov_b32_e32 v24, 0
	v_mov_b32_e32 v25, 0
	v_mov_b32_e32 v26, 0
	v_mov_b32_e32 v27, 0
	v_mov_b32_e32 v28, 0
	v_mov_b32_e32 v29, 0
	v_mov_b32_e32 v30, 0
	v_mov_b32_e32 v31, 0
	v_mov_b32_e32 v20, 0
	v_mov_b32_e32 v21, 0
	v_mov_b32_e32 v22, 0
	v_mov_b32_e32 v23, 0
	s_and_saveexec_b64 s[10:11], s[6:7]
	v_lshl_or_b32 v222, v152, 6, v183
	v_lshlrev_b32_e32 v222, 9, v222
	v_lshl_add_u32 v222, v132, 2, v222
	v_add_u32_e32 v223, 0x4000, v222
	global_load_dwordx2 v[218:219], v222, s[78:79]
	global_load_dwordx2 v[220:221], v223, s[78:79]
	s_or_b64 exec, exec, s[10:11]
	s_and_saveexec_b64 s[8:9], s[4:5]
	s_cbranch_execz .Ls5c_u_skip
	v_lshlrev_b64 v[2:3], 11, v[148:149]
	v_lshl_add_u64 v[10:11], v[0:1], 0, v[2:3]
	global_load_dwordx4 v[184:187], v[10:11], off
	global_load_dwordx4 v[188:191], v[10:11], off offset:16
	v_lshlrev_b64 v[2:3], 11, v[146:147]
	v_lshl_add_u64 v[10:11], v[0:1], 0, v[2:3]
	global_load_dwordx4 v[192:195], v[10:11], off
	global_load_dwordx4 v[196:199], v[10:11], off offset:16
	v_lshlrev_b64 v[2:3], 11, v[144:145]
	v_lshl_add_u64 v[10:11], v[0:1], 0, v[2:3]
	global_load_dwordx4 v[200:203], v[10:11], off
	global_load_dwordx4 v[204:207], v[10:11], off offset:16
	v_lshlrev_b64 v[2:3], 11, v[142:143]
	v_lshl_add_u64 v[10:11], v[0:1], 0, v[2:3]
	global_load_dwordx4 v[208:211], v[10:11], off
	global_load_dwordx4 v[212:215], v[10:11], off offset:16
.Ls5c_u_skip:
	s_or_b64 exec, exec, s[8:9]
	v_lshlrev_b32_e32 v120, 13, v183
	v_lshl_or_b32 v2, v183, 10, v122
	v_lshl_add_u64 v[0:1], v[124:125], 0, v[120:121]
	global_load_dwordx4 v[84:87], v2, s[58:59]
	global_load_dwordx4 v[116:119], v[0:1], off
	global_load_dwordx4 v[112:115], v[0:1], off offset:1024
	global_load_dwordx4 v[108:111], v[0:1], off offset:2048
	v_add_co_u32_e32 v2, vcc, 0x1000, v0
	v_lshlrev_b32_e32 v120, 12, v183
	s_nop 0
	v_addc_co_u32_e32 v3, vcc, 0, v1, vcc
	global_load_dwordx4 v[104:107], v[0:1], off offset:3072
	global_load_dwordx4 v[100:103], v[2:3], off
	global_load_dwordx4 v[96:99], v[2:3], off offset:1024
	global_load_dwordx4 v[88:91], v[2:3], off offset:2048
	v_lshl_add_u64 v[0:1], v[126:127], 0, v[120:121]
	global_load_dwordx4 v[92:95], v[2:3], off offset:3072
	global_load_dwordx4 v[76:79], v[0:1], off
	global_load_dwordx4 v[80:83], v[0:1], off offset:1024
	global_load_dwordx4 v[68:71], v[0:1], off offset:2048
	v_or_b32_e32 v2, 32, v183
	v_lshlrev_b32_e32 v120, 13, v2
	v_lshl_or_b32 v3, v2, 10, v122
	global_load_dwordx4 v[72:75], v[0:1], off offset:3072
	global_load_dwordx4 v[16:19], v3, s[58:59]
	v_lshl_add_u64 v[0:1], v[124:125], 0, v[120:121]
	global_load_dwordx4 v[64:67], v[0:1], off
	global_load_dwordx4 v[60:63], v[0:1], off offset:1024
	global_load_dwordx4 v[56:59], v[0:1], off offset:2048
	global_load_dwordx4 v[52:55], v[0:1], off offset:3072
	v_add_co_u32_e32 v0, vcc, s45, v0
	v_lshlrev_b32_e32 v120, 12, v2
	s_nop 0
	v_addc_co_u32_e32 v1, vcc, 0, v1, vcc
	global_load_dwordx4 v[44:47], v[0:1], off
	global_load_dwordx4 v[40:43], v[0:1], off offset:1024
	global_load_dwordx4 v[36:39], v[0:1], off offset:2048
	global_load_dwordx4 v[32:35], v[0:1], off offset:3072
	v_lshl_add_u64 v[0:1], v[126:127], 0, v[120:121]
	global_load_dwordx4 v[8:11], v[0:1], off
	global_load_dwordx4 v[12:15], v[0:1], off offset:1024
	global_load_dwordx4 v[4:7], v[0:1], off offset:2048
	s_nop 0
	global_load_dwordx4 v[0:3], v[0:1], off offset:3072
	s_and_saveexec_b64 s[8:9], s[4:5]
	s_waitcnt vmcnt(26)
	v_cvt_pk_bf16_f32 v48, v184, v185
	v_cvt_pk_bf16_f32 v49, v186, v187
	v_cvt_pk_bf16_f32 v50, v188, v189
	v_cvt_pk_bf16_f32 v51, v190, v191
	v_cvt_pk_bf16_f32 v24, v192, v193
	v_cvt_pk_bf16_f32 v25, v194, v195
	v_cvt_pk_bf16_f32 v26, v196, v197
	v_cvt_pk_bf16_f32 v27, v198, v199
	v_cvt_pk_bf16_f32 v28, v200, v201
	v_cvt_pk_bf16_f32 v29, v202, v203
	v_cvt_pk_bf16_f32 v30, v204, v205
	v_cvt_pk_bf16_f32 v31, v206, v207
	v_cvt_pk_bf16_f32 v20, v208, v209
	v_cvt_pk_bf16_f32 v21, v210, v211
	v_cvt_pk_bf16_f32 v22, v212, v213
	v_cvt_pk_bf16_f32 v23, v214, v215
	s_or_b64 exec, exec, s[8:9]
	v_lshl_or_b32 v158, v152, 6, v183
	v_mov_b32_e32 v120, v121
	v_ashrrev_i32_e32 v159, 31, v158
	v_lshlrev_b32_e32 v156, 2, v132
	v_mov_b64_e32 v[160:161], v[120:121]
	s_and_saveexec_b64 s[8:9], s[6:7]
	s_cbranch_execz .LBB0_1100
	v_pk_mov_b32 v[160:161], v[218:219], v[218:219] op_sel:[1,0]

.LBB0_1108:
	s_or_b64 exec, exec, s[8:9]
	v_mov_b32_e32 v120, v121
	v_or_b32_e32 v72, 32, v158
	v_ashrrev_i32_e32 v73, 31, v72
	v_mov_b64_e32 v[74:75], v[120:121]
	s_and_saveexec_b64 s[8:9], s[6:7]
	s_cbranch_execz .LBB0_1110
	v_pk_mov_b32 v[74:75], v[220:221], v[220:221] op_sel:[1,0]
